# P1: per-tile accumulator zeroing (128 v_mov) removed; peeled first K iteration starts every accumulator tile from C=0
# speedup vs baseline: 1.0054x; 1.0007x over previous
.LBB0_187:
	s_add_u32 s14, s4, 0x100
	s_addc_u32 s15, s5, 0
	s_mov_b32 s16, -2
	ds_read_b128 v[128:131], v168
	ds_read_b128 v[152:155], v168 offset:1024
	ds_read_b128 v[180:183], v168 offset:2048
	ds_read_b128 v[184:187], v168 offset:3072
	ds_read_b128 v[188:191], v169
	ds_read_b128 v[192:195], v169 offset:1024
	ds_read_b128 v[196:199], v169 offset:2048
	ds_read_b128 v[200:203], v169 offset:3072
	s_add_u32 s4, s0, 0x100
	s_addc_u32 s5, s1, 0
	s_cmp_eq_u32 s16, 12
	s_cselect_b32 s13, s95, s5
	s_cselect_b32 s12, s94, s4
	s_cselect_b32 s11, s97, s15
	s_cselect_b32 s10, s96, s14
	v_lshl_add_u64 v[156:157], s[0:1], 0, v[144:145]
	s_add_i32 m0, s89, 0xc000
	ds_read_b128 v[204:207], v170
	ds_read_b128 v[208:211], v170 offset:1024
	ds_read_b128 v[212:215], v170 offset:2048
	ds_read_b128 v[216:219], v170 offset:3072
	ds_read_b128 v[220:223], v170 offset:4096
	ds_read_b128 v[224:227], v170 offset:5120
	ds_read_b128 v[228:231], v170 offset:6144
	ds_read_b128 v[232:235], v170 offset:7168
	global_load_lds_dwordx4 v[156:157], off
	v_lshl_add_u64 v[156:157], s[0:1], 0, v[146:147]
	s_add_i32 m0, s89, 0xe000
	s_nop 0
	global_load_lds_dwordx4 v[156:157], off
	s_waitcnt vmcnt(8)
	s_waitcnt lgkmcnt(0)
	s_barrier
	s_setprio 1
	s_waitcnt lgkmcnt(0)
	v_mfma_f32_16x16x32_f16 v[84:87], v[128:131], v[204:207], 0
	v_mfma_f32_16x16x32_f16 v[92:95], v[180:183], v[204:207], 0
	v_mfma_f32_16x16x32_f16 v[68:71], v[128:131], v[212:215], 0
	v_mfma_f32_16x16x32_f16 v[76:79], v[180:183], v[212:215], 0
	v_mfma_f32_16x16x32_f16 v[52:55], v[128:131], v[220:223], 0
	v_mfma_f32_16x16x32_f16 v[124:127], v[180:183], v[220:223], 0
	v_mfma_f32_16x16x32_f16 v[60:63], v[128:131], v[228:231], 0
	v_mfma_f32_16x16x32_f16 v[116:119], v[180:183], v[228:231], 0
	v_mfma_f32_16x16x32_f16 v[84:87], v[152:155], v[208:211], v[84:87]
	v_mfma_f32_16x16x32_f16 v[92:95], v[184:187], v[208:211], v[92:95]
	v_mfma_f32_16x16x32_f16 v[68:71], v[152:155], v[216:219], v[68:71]
	v_mfma_f32_16x16x32_f16 v[76:79], v[184:187], v[216:219], v[76:79]
	v_mfma_f32_16x16x32_f16 v[52:55], v[152:155], v[224:227], v[52:55]
	v_mfma_f32_16x16x32_f16 v[124:127], v[184:187], v[224:227], v[124:127]
	v_mfma_f32_16x16x32_f16 v[60:63], v[152:155], v[232:235], v[60:63]
	v_mfma_f32_16x16x32_f16 v[116:119], v[184:187], v[232:235], v[116:119]
	s_setprio 0
	s_setprio 1
	v_mfma_f32_16x16x32_f16 v[88:91], v[188:191], v[204:207], 0
	v_mfma_f32_16x16x32_f16 v[80:83], v[196:199], v[204:207], 0
	v_mfma_f32_16x16x32_f16 v[72:75], v[188:191], v[212:215], 0
	v_mfma_f32_16x16x32_f16 v[64:67], v[196:199], v[212:215], 0
	v_mfma_f32_16x16x32_f16 v[120:123], v[188:191], v[220:223], 0
	v_mfma_f32_16x16x32_f16 v[48:51], v[196:199], v[220:223], 0
	v_mfma_f32_16x16x32_f16 v[112:115], v[188:191], v[228:231], 0
	v_mfma_f32_16x16x32_f16 v[56:59], v[196:199], v[228:231], 0
	v_mfma_f32_16x16x32_f16 v[88:91], v[192:195], v[208:211], v[88:91]
	v_mfma_f32_16x16x32_f16 v[80:83], v[200:203], v[208:211], v[80:83]
	v_mfma_f32_16x16x32_f16 v[72:75], v[192:195], v[216:219], v[72:75]
	v_mfma_f32_16x16x32_f16 v[64:67], v[200:203], v[216:219], v[64:67]
	v_mfma_f32_16x16x32_f16 v[120:123], v[192:195], v[224:227], v[120:123]
	v_mfma_f32_16x16x32_f16 v[48:51], v[200:203], v[224:227], v[48:51]
	v_mfma_f32_16x16x32_f16 v[112:115], v[192:195], v[232:235], v[112:115]
	v_mfma_f32_16x16x32_f16 v[56:59], v[200:203], v[232:235], v[56:59]
	s_setprio 0
	s_barrier
	s_add_i32 s0, s23, s88
	v_lshl_add_u64 v[156:157], s[10:11], 0, v[134:135]
	s_mov_b32 m0, s0
	ds_read_b128 v[204:207], v170 offset:16384
	ds_read_b128 v[208:211], v170 offset:17408
	ds_read_b128 v[212:215], v170 offset:18432
	ds_read_b128 v[216:219], v170 offset:19456
	ds_read_b128 v[220:223], v170 offset:20480
	ds_read_b128 v[224:227], v170 offset:21504
	ds_read_b128 v[228:231], v170 offset:22528
	ds_read_b128 v[232:235], v170 offset:23552
	global_load_lds_dwordx4 v[156:157], off
	s_add_i32 m0, s0, 0x2000
	s_add_u32 s0, s10, 0x40000
	v_lshl_add_u64 v[236:237], s[10:11], 0, v[138:139]
	s_addc_u32 s1, s11, 0
	s_add_i32 s17, s22, s88
	global_load_lds_dwordx4 v[236:237], off
	v_lshl_add_u64 v[238:239], s[0:1], 0, v[134:135]
	s_mov_b32 m0, s17
	v_lshl_add_u64 v[240:241], s[12:13], 0, v[136:137]
	global_load_lds_dwordx4 v[238:239], off
	v_lshl_add_u64 v[238:239], s[0:1], 0, v[138:139]
	s_add_i32 m0, s17, 0x2000
	s_nop 0
	global_load_lds_dwordx4 v[238:239], off
	v_lshl_add_u64 v[238:239], s[12:13], 0, v[132:133]
	s_mov_b32 m0, s89
	s_nop 0
	global_load_lds_dwordx4 v[238:239], off
	s_mov_b32 m0, s3
	s_nop 0
	global_load_lds_dwordx4 v[240:241], off
	s_waitcnt vmcnt(8)
	s_waitcnt lgkmcnt(0)
	s_barrier
	s_setprio 1
	s_waitcnt lgkmcnt(0)
	v_mfma_f32_16x16x32_f16 v[36:39], v[128:131], v[204:207], 0
	v_mfma_f32_16x16x32_f16 v[44:47], v[180:183], v[204:207], 0
	v_mfma_f32_16x16x32_f16 v[20:23], v[128:131], v[212:215], 0
	v_mfma_f32_16x16x32_f16 v[32:35], v[180:183], v[212:215], 0
	v_mfma_f32_16x16x32_f16 v[4:7], v[128:131], v[220:223], 0
	v_mfma_f32_16x16x32_f16 v[108:111], v[180:183], v[220:223], 0
	v_mfma_f32_16x16x32_f16 v[12:15], v[128:131], v[228:231], 0
	v_mfma_f32_16x16x32_f16 v[100:103], v[180:183], v[228:231], 0
	v_mfma_f32_16x16x32_f16 v[36:39], v[152:155], v[208:211], v[36:39]
	v_mfma_f32_16x16x32_f16 v[44:47], v[184:187], v[208:211], v[44:47]
	v_mfma_f32_16x16x32_f16 v[20:23], v[152:155], v[216:219], v[20:23]
	v_mfma_f32_16x16x32_f16 v[32:35], v[184:187], v[216:219], v[32:35]
	v_mfma_f32_16x16x32_f16 v[4:7], v[152:155], v[224:227], v[4:7]
	v_mfma_f32_16x16x32_f16 v[108:111], v[184:187], v[224:227], v[108:111]
	v_mfma_f32_16x16x32_f16 v[12:15], v[152:155], v[232:235], v[12:15]
	v_mfma_f32_16x16x32_f16 v[100:103], v[184:187], v[232:235], v[100:103]
	s_setprio 0
	s_setprio 1
	v_mfma_f32_16x16x32_f16 v[40:43], v[188:191], v[204:207], 0
	v_mfma_f32_16x16x32_f16 v[28:31], v[196:199], v[204:207], 0
	v_mfma_f32_16x16x32_f16 v[24:27], v[188:191], v[212:215], 0
	v_mfma_f32_16x16x32_f16 v[16:19], v[196:199], v[212:215], 0
	v_mfma_f32_16x16x32_f16 v[104:107], v[188:191], v[220:223], 0
	v_mfma_f32_16x16x32_f16 v[0:3], v[196:199], v[220:223], 0
	v_mfma_f32_16x16x32_f16 v[96:99], v[188:191], v[228:231], 0
	v_mfma_f32_16x16x32_f16 v[8:11], v[196:199], v[228:231], 0
	v_mfma_f32_16x16x32_f16 v[40:43], v[192:195], v[208:211], v[40:43]
	v_mfma_f32_16x16x32_f16 v[28:31], v[200:203], v[208:211], v[28:31]
	v_mfma_f32_16x16x32_f16 v[24:27], v[192:195], v[216:219], v[24:27]
	v_mfma_f32_16x16x32_f16 v[16:19], v[200:203], v[216:219], v[16:19]
	v_mfma_f32_16x16x32_f16 v[104:107], v[192:195], v[224:227], v[104:107]
	v_mfma_f32_16x16x32_f16 v[0:3], v[200:203], v[224:227], v[0:3]
	v_mfma_f32_16x16x32_f16 v[96:99], v[192:195], v[232:235], v[96:99]
	v_mfma_f32_16x16x32_f16 v[8:11], v[200:203], v[232:235], v[8:11]
	s_setprio 0
	s_barrier
	ds_read_b128 v[128:131], v171
	ds_read_b128 v[152:155], v171 offset:1024
	ds_read_b128 v[180:183], v171 offset:2048
	ds_read_b128 v[184:187], v171 offset:3072
	ds_read_b128 v[188:191], v172
	ds_read_b128 v[192:195], v172 offset:1024
	ds_read_b128 v[196:199], v172 offset:2048
	ds_read_b128 v[200:203], v172 offset:3072
	s_add_u32 s0, s12, 0x40000
	s_addc_u32 s1, s13, 0
	s_mov_b32 m0, s33
	v_lshl_add_u64 v[242:243], s[0:1], 0, v[132:133]
	ds_read_b128 v[204:207], v170 offset:32768
	ds_read_b128 v[208:211], v170 offset:33792
	ds_read_b128 v[212:215], v170 offset:34816
	ds_read_b128 v[216:219], v170 offset:35840
	ds_read_b128 v[220:223], v170 offset:36864
	ds_read_b128 v[224:227], v170 offset:37888
	ds_read_b128 v[228:231], v170 offset:38912
	ds_read_b128 v[232:235], v170 offset:39936
	global_load_lds_dwordx4 v[242:243], off
	v_lshl_add_u64 v[242:243], s[0:1], 0, v[136:137]
	s_mov_b32 m0, s50
	s_nop 0
	global_load_lds_dwordx4 v[242:243], off
	s_waitcnt vmcnt(8)
	s_waitcnt lgkmcnt(0)
	s_barrier
	s_setprio 1
	s_waitcnt lgkmcnt(0)
	v_mfma_f32_16x16x32_f16 v[84:87], v[128:131], v[204:207], v[84:87]
	v_mfma_f32_16x16x32_f16 v[92:95], v[180:183], v[204:207], v[92:95]
	v_mfma_f32_16x16x32_f16 v[68:71], v[128:131], v[212:215], v[68:71]
	v_mfma_f32_16x16x32_f16 v[76:79], v[180:183], v[212:215], v[76:79]
	v_mfma_f32_16x16x32_f16 v[52:55], v[128:131], v[220:223], v[52:55]
	v_mfma_f32_16x16x32_f16 v[124:127], v[180:183], v[220:223], v[124:127]
	v_mfma_f32_16x16x32_f16 v[60:63], v[128:131], v[228:231], v[60:63]
	v_mfma_f32_16x16x32_f16 v[116:119], v[180:183], v[228:231], v[116:119]
	v_mfma_f32_16x16x32_f16 v[84:87], v[152:155], v[208:211], v[84:87]
	v_mfma_f32_16x16x32_f16 v[92:95], v[184:187], v[208:211], v[92:95]
	v_mfma_f32_16x16x32_f16 v[68:71], v[152:155], v[216:219], v[68:71]
	v_mfma_f32_16x16x32_f16 v[76:79], v[184:187], v[216:219], v[76:79]
	v_mfma_f32_16x16x32_f16 v[52:55], v[152:155], v[224:227], v[52:55]
	v_mfma_f32_16x16x32_f16 v[124:127], v[184:187], v[224:227], v[124:127]
	v_mfma_f32_16x16x32_f16 v[60:63], v[152:155], v[232:235], v[60:63]
	v_mfma_f32_16x16x32_f16 v[116:119], v[184:187], v[232:235], v[116:119]
	s_setprio 0
	s_setprio 1
	v_mfma_f32_16x16x32_f16 v[88:91], v[188:191], v[204:207], v[88:91]
	v_mfma_f32_16x16x32_f16 v[80:83], v[196:199], v[204:207], v[80:83]
	v_mfma_f32_16x16x32_f16 v[72:75], v[188:191], v[212:215], v[72:75]
	v_mfma_f32_16x16x32_f16 v[64:67], v[196:199], v[212:215], v[64:67]
	v_mfma_f32_16x16x32_f16 v[120:123], v[188:191], v[220:223], v[120:123]
	v_mfma_f32_16x16x32_f16 v[48:51], v[196:199], v[220:223], v[48:51]
	v_mfma_f32_16x16x32_f16 v[112:115], v[188:191], v[228:231], v[112:115]
	v_mfma_f32_16x16x32_f16 v[56:59], v[196:199], v[228:231], v[56:59]
	v_mfma_f32_16x16x32_f16 v[88:91], v[192:195], v[208:211], v[88:91]
	v_mfma_f32_16x16x32_f16 v[80:83], v[200:203], v[208:211], v[80:83]
	v_mfma_f32_16x16x32_f16 v[72:75], v[192:195], v[216:219], v[72:75]
	v_mfma_f32_16x16x32_f16 v[64:67], v[200:203], v[216:219], v[64:67]
	v_mfma_f32_16x16x32_f16 v[120:123], v[192:195], v[224:227], v[120:123]
	v_mfma_f32_16x16x32_f16 v[48:51], v[200:203], v[224:227], v[48:51]
	v_mfma_f32_16x16x32_f16 v[112:115], v[192:195], v[232:235], v[112:115]
	v_mfma_f32_16x16x32_f16 v[56:59], v[200:203], v[232:235], v[56:59]
	s_setprio 0
	s_barrier
	s_add_i32 s0, s36, s88
	v_lshl_add_u64 v[156:157], v[156:157], 0, s[26:27]
	s_mov_b32 m0, s0
	ds_read_b128 v[204:207], v170 offset:49152
	ds_read_b128 v[208:211], v170 offset:50176
	ds_read_b128 v[212:215], v170 offset:51200
	ds_read_b128 v[216:219], v170 offset:52224
	ds_read_b128 v[220:223], v170 offset:53248
	ds_read_b128 v[224:227], v170 offset:54272
	ds_read_b128 v[228:231], v170 offset:55296
	ds_read_b128 v[232:235], v170 offset:56320
	global_load_lds_dwordx4 v[156:157], off
	s_add_i32 m0, s0, 0x2000
	s_add_u32 s0, s10, 0x40080
	v_lshl_add_u64 v[156:157], v[236:237], 0, s[26:27]
	s_addc_u32 s1, s11, 0
	s_add_i32 s10, s37, s88
	global_load_lds_dwordx4 v[156:157], off
	v_lshl_add_u64 v[156:157], s[0:1], 0, v[134:135]
	s_mov_b32 m0, s10
	s_nop 0
	global_load_lds_dwordx4 v[156:157], off
	v_lshl_add_u64 v[156:157], s[0:1], 0, v[138:139]
	s_add_i32 m0, s10, 0x2000
	s_nop 0
	global_load_lds_dwordx4 v[156:157], off
	v_lshl_add_u64 v[156:157], v[238:239], 0, s[26:27]
	s_mov_b32 m0, s51
	s_nop 0
	global_load_lds_dwordx4 v[156:157], off
	v_lshl_add_u64 v[156:157], v[240:241], 0, s[26:27]
	s_mov_b32 m0, s82
	s_nop 0
	global_load_lds_dwordx4 v[156:157], off
	s_waitcnt vmcnt(8)
	s_waitcnt lgkmcnt(0)
	s_barrier
	s_setprio 1
	s_waitcnt lgkmcnt(0)
	v_mfma_f32_16x16x32_f16 v[36:39], v[128:131], v[204:207], v[36:39]
	v_mfma_f32_16x16x32_f16 v[44:47], v[180:183], v[204:207], v[44:47]
	v_mfma_f32_16x16x32_f16 v[20:23], v[128:131], v[212:215], v[20:23]
	v_mfma_f32_16x16x32_f16 v[32:35], v[180:183], v[212:215], v[32:35]
	v_mfma_f32_16x16x32_f16 v[4:7], v[128:131], v[220:223], v[4:7]
	v_mfma_f32_16x16x32_f16 v[108:111], v[180:183], v[220:223], v[108:111]
	v_mfma_f32_16x16x32_f16 v[12:15], v[128:131], v[228:231], v[12:15]
	v_mfma_f32_16x16x32_f16 v[100:103], v[180:183], v[228:231], v[100:103]
	v_mfma_f32_16x16x32_f16 v[36:39], v[152:155], v[208:211], v[36:39]
	v_mfma_f32_16x16x32_f16 v[44:47], v[184:187], v[208:211], v[44:47]
	v_mfma_f32_16x16x32_f16 v[20:23], v[152:155], v[216:219], v[20:23]
	v_mfma_f32_16x16x32_f16 v[32:35], v[184:187], v[216:219], v[32:35]
	v_mfma_f32_16x16x32_f16 v[4:7], v[152:155], v[224:227], v[4:7]
	v_mfma_f32_16x16x32_f16 v[108:111], v[184:187], v[224:227], v[108:111]
	v_mfma_f32_16x16x32_f16 v[12:15], v[152:155], v[232:235], v[12:15]
	v_mfma_f32_16x16x32_f16 v[100:103], v[184:187], v[232:235], v[100:103]
	s_setprio 0
	s_setprio 1
	v_mfma_f32_16x16x32_f16 v[40:43], v[188:191], v[204:207], v[40:43]
	v_mfma_f32_16x16x32_f16 v[28:31], v[196:199], v[204:207], v[28:31]
	v_mfma_f32_16x16x32_f16 v[24:27], v[188:191], v[212:215], v[24:27]
	v_mfma_f32_16x16x32_f16 v[16:19], v[196:199], v[212:215], v[16:19]
	v_mfma_f32_16x16x32_f16 v[104:107], v[188:191], v[220:223], v[104:107]
	v_mfma_f32_16x16x32_f16 v[0:3], v[196:199], v[220:223], v[0:3]
	v_mfma_f32_16x16x32_f16 v[96:99], v[188:191], v[228:231], v[96:99]
	v_mfma_f32_16x16x32_f16 v[8:11], v[196:199], v[228:231], v[8:11]
	v_mfma_f32_16x16x32_f16 v[40:43], v[192:195], v[208:211], v[40:43]
	v_mfma_f32_16x16x32_f16 v[28:31], v[200:203], v[208:211], v[28:31]
	v_mfma_f32_16x16x32_f16 v[24:27], v[192:195], v[216:219], v[24:27]
	v_mfma_f32_16x16x32_f16 v[16:19], v[200:203], v[216:219], v[16:19]
	v_mfma_f32_16x16x32_f16 v[104:107], v[192:195], v[224:227], v[104:107]
	v_mfma_f32_16x16x32_f16 v[0:3], v[200:203], v[224:227], v[0:3]
	v_mfma_f32_16x16x32_f16 v[96:99], v[192:195], v[232:235], v[96:99]
	v_mfma_f32_16x16x32_f16 v[8:11], v[200:203], v[232:235], v[8:11]
	s_setprio 0
	s_barrier
	s_add_i32 s16, s16, 2
	s_add_u32 s14, s14, 0x100
	s_addc_u32 s15, s15, 0
	s_cmp_gt_u32 s16, 13
	s_mov_b64 s[0:1], s[4:5]

.LBB0_537:
	s_or_b64 exec, exec, s[0:1]
	s_and_b64 s[0:1], s[36:37], exec
	s_cselect_b32 s28, 16, 0x1000
	s_add_u32 s64, s76, 0x13d00000
	s_addc_u32 s65, s77, 0
	s_bfe_u32 s68, s96, 0x20006
	s_mul_i32 s0, s68, 0x3700
	s_add_i32 s71, s0, 0
	s_and_b32 s0, s96, 0xffffff00
	s_lshr_b32 s74, s96, 8
	s_add_i32 s84, s0, 0
	s_lshl_b32 s11, s74, 5
	s_add_i32 s80, s84, 0x12600
	s_cmpk_lt_u32 s96, 0x540
	v_readlane_b32 s20, v255, 31
	s_cselect_b64 s[40:41], -1, 0
	s_add_i32 s12, s20, -4
	s_lshl_b32 s13, s12, 2
	s_lshl_b32 s22, s12, 10
	s_cmpk_lt_u32 s96, 0x440
	s_cselect_b64 s[42:43], -1, 0
	s_lshl_b32 s66, s20, 10
	s_cmpk_lt_u32 s96, 0x340
	s_cselect_b64 s[46:47], -1, 0
	s_add_i32 s14, s20, 4
	s_lshl_b32 s15, s14, 2
	s_lshl_b32 s23, s14, 10
	s_cmpk_lt_u32 s96, 0x240
	s_cselect_b64 s[48:49], -1, 0
	s_add_i32 s16, s20, 8
	s_lshl_b32 s17, s16, 2
	s_lshl_b32 s24, s16, 10
	s_cmp_eq_u32 s20, 4
	s_cselect_b64 s[50:51], -1, 0
	s_cmp_eq_u32 s20, 2
	s_mov_b32 s0, 0xfc00000
	s_cselect_b32 s38, s0, 0x13d00000
	s_add_u32 s8, s76, s6
	s_addc_u32 s9, s77, 0
	s_mul_i32 s0, s20, 0x2400
	s_add_i32 s1, 0, 0x1a900
	s_add_i32 s81, s1, s0
	s_lshl_b32 s0, s74, 7
	s_add_i32 s83, s0, 0
	s_add_i32 s82, s81, 0x2000
	s_add_i32 s83, s83, 0x14800
	s_add_i32 s84, s84, 0x12400
	s_lshl_b32 s29, s20, 5
	s_add_u32 s6, s64, s6
	s_addc_u32 s7, s65, 0
	s_lshl_b32 s85, s33, 10
	s_add_u32 s18, s76, 0x10000
	v_writelane_b32 v255, s96, 33
	s_addc_u32 s19, s77, 0
	v_lshl_or_b32 v11, s68, 4, v9
	v_writelane_b32 v255, s18, 34
	v_add_u32_e32 v25, 1, v11
	v_lshlrev_b32_e32 v27, 3, v38
	v_writelane_b32 v255, s19, 35
	v_lshlrev_b32_e32 v10, 7, v25
	v_and_b32_e32 v22, 8, v27
	s_add_i32 s0, 0, 0x1cd00
	s_add_i32 s18, 0, 0x1f100
	v_add3_u32 v91, s1, v10, v22
	v_add3_u32 v92, s0, v10, v22
	v_add3_u32 v93, s18, v10, v22
	v_lshlrev_b32_e32 v10, 8, v25
	s_add_i32 s19, 0, 0x23900
	v_add3_u32 v28, s19, v10, v22
	v_lshlrev_b32_e32 v10, 7, v11
	v_add3_u32 v94, s1, v10, v22
	v_add3_u32 v95, s0, v10, v22
	v_add3_u32 v96, s18, v10, v22
	v_lshlrev_b32_e32 v10, 8, v11
	v_add3_u32 v29, s19, v10, v22
	v_add_u32_e32 v10, 1, v89
	s_add_i32 s19, 0, 0x21500
	v_lshl_add_u32 v32, v10, 7, s19
	v_xor_b32_e32 v10, v10, v39
	v_lshlrev_b32_e32 v10, 4, v10
	v_and_b32_e32 v33, 0x70, v10
	v_lshlrev_b32_e32 v10, 7, v89
	v_add_u32_e32 v34, s19, v10
	s_add_i32 s19, 0, 0x12800
	s_cmp_lg_u32 s12, 16
	v_add_u32_e32 v36, s19, v10
	v_or_b32_e32 v10, s13, v38
	s_cselect_b64 vcc, -1, 0
	v_xor_b32_e32 v22, v89, v39
	v_cndmask_b32_e32 v98, 64, v10, vcc
	v_bitop3_b32 v10, v38, v39, s13 bitop3:0x36
	v_lshlrev_b32_e32 v22, 4, v22
	v_and_or_b32 v10, v10, 7, v41
	v_and_b32_e32 v35, 0x70, v22
	v_lshlrev_b32_e32 v22, 4, v10
	v_mov_b32_e32 v10, 0
	v_mov_b32_e32 v23, v10
	s_cmp_lg_u32 s20, 16
	v_lshl_add_u64 v[48:49], s[4:5], 0, v[22:23]
	v_or_b32_e32 v22, s3, v38
	s_cselect_b64 vcc, -1, 0
	v_cndmask_b32_e32 v99, 64, v22, vcc
	v_bitop3_b32 v22, v38, v39, s3 bitop3:0x36
	v_and_or_b32 v22, v22, 7, v41
	v_lshlrev_b32_e32 v22, 4, v22
	s_cmp_lg_u32 s14, 16
	v_lshl_add_u64 v[50:51], s[4:5], 0, v[22:23]
	v_or_b32_e32 v22, s15, v38
	s_cselect_b64 vcc, -1, 0
	v_cndmask_b32_e32 v100, 64, v22, vcc
	v_bitop3_b32 v22, v38, v39, s15 bitop3:0x36
	v_and_or_b32 v22, v22, 7, v41
	v_lshlrev_b32_e32 v22, 4, v22
	s_cmp_lg_u32 s16, 16
	v_lshl_add_u64 v[52:53], s[4:5], 0, v[22:23]
	v_or_b32_e32 v22, s17, v38
	s_cselect_b64 vcc, -1, 0
	v_cndmask_b32_e32 v101, 64, v22, vcc
	v_bitop3_b32 v22, v38, v39, s17 bitop3:0x36
	v_and_or_b32 v22, v22, 7, v41
	v_lshlrev_b32_e32 v22, 4, v22
	v_lshl_add_u64 v[54:55], s[4:5], 0, v[22:23]
	v_xor_b32_e32 v22, v38, v20
	s_movk_i32 s10, 0x3700
	v_or_b32_e32 v22, v22, v41
	v_lshlrev_b32_e32 v41, 5, v9
	v_lshrrev_b32_e32 v45, 7, v42
	v_cmp_gt_u32_e64 s[0:1], 16, v40
	v_or_b32_e32 v103, v27, v41
	v_lshl_add_u32 v104, v40, 2, s71
	v_add_u32_e32 v40, s71, v41
	v_lshrrev_b32_e32 v41, 2, v9
	v_mul_lo_u32 v45, v45, s10
	v_or_b32_e32 v41, v90, v41
	v_add_u32_e32 v67, 0, v45
	v_bfe_u32 v45, v42, 3, 4
	v_mul_u32_u24_e32 v41, 0x48, v41
	v_and_b32_e32 v21, 12, v21
	v_mul_u32_u24_e32 v45, 0x48, v45
	v_or_b32_e32 v24, s11, v90
	v_add_lshl_u32 v105, v21, v41, 1
	v_lshl_or_b32 v21, v89, 6, v8
	v_add_lshl_u32 v8, v45, v8, 1
	v_mov_b32_e32 v45, v10
	v_and_b32_e32 v26, 7, v25
	v_lshl_add_u64 v[60:61], s[6:7], 0, v[44:45]
	v_cmp_eq_u32_e64 s[6:7], 0, v42
	v_lshrrev_b32_e32 v42, 3, v24
	v_and_b32_e32 v62, 8, v42
	v_bitop3_b32 v63, v42, v26, 5 bitop3:0x6c
	v_or_b32_e32 v63, v63, v62
	v_lshlrev_b32_e32 v68, 4, v63
	v_add_u32_e32 v63, 64, v24
	v_bitop3_b32 v45, v42, v25, 7 bitop3:0x78
	v_lshrrev_b32_e32 v64, 3, v63
	v_xor_b32_e32 v69, v42, v20
	v_bitop3_b32 v42, v42, v20, 5 bitop3:0x6c
	v_and_b32_e32 v65, 8, v64
	v_or_b32_e32 v42, v42, v62
	v_bitop3_b32 v62, v64, v20, 5 bitop3:0x6c
	v_or_b32_e32 v62, v62, v65
	v_lshlrev_b32_e32 v108, 4, v69
	v_lshlrev_b32_e32 v69, 4, v62
	v_or_b32_e32 v62, 16, v24
	v_lshlrev_b32_e32 v22, 4, v22
	v_lshlrev_b32_e32 v71, 1, v63
	v_lshrrev_b32_e32 v63, 3, v62
	v_lshl_add_u64 v[56:57], s[4:5], 0, v[22:23]
	v_xor_b32_e32 v22, v88, v20
	v_bitop3_b32 v26, v64, v26, 5 bitop3:0x6c
	v_bitop3_b32 v64, v63, v25, 7 bitop3:0x78
	v_lshlrev_b32_e32 v22, 4, v22
	v_or_b32_e32 v26, v26, v65
	v_lshlrev_b32_e32 v111, 4, v64
	v_and_b32_e32 v64, 8, v63
	v_bitop3_b32 v65, v63, v25, 7 bitop3:0x28
	s_movk_i32 s18, 0x48
	v_lshl_add_u64 v[58:59], s[8:9], 0, v[22:23]
	v_or_b32_e32 v23, s11, v9
	v_or_b32_e32 v65, v65, v64
	v_mul_u32_u24_e32 v30, 0x48, v11
	v_mul_u32_u24_e32 v31, 0x48, v9
	v_lshlrev_b32_e32 v97, 2, v11
	v_or_b32_e32 v22, 16, v90
	v_lshlrev_b32_e32 v72, 4, v65
	v_add_u32_e32 v65, 0x50, v24
	v_mul_lo_u32 v23, v23, s18
	v_mad_u32_u24 v11, v11, s18, 32
	v_lshlrev_b32_e32 v70, 1, v24
	v_add_lshl_u32 v109, v24, v30, 1
	v_add_lshl_u32 v110, v24, v31, 1
	v_lshrrev_b32_e32 v73, 3, v65
	v_xor_b32_e32 v75, v63, v20
	v_bitop3_b32 v63, v63, v20, 7 bitop3:0x6c
	v_add_lshl_u32 v113, v62, v30, 1
	v_add_lshl_u32 v115, v30, v90, 1
	v_add_lshl_u32 v116, v22, v30, 1
	v_add_u32_e32 v30, 0x480, v23
	v_add_lshl_u32 v119, v11, v90, 1
	v_add_lshl_u32 v120, v11, v22, 1
	v_or_b32_e32 v11, 32, v90
	v_lshlrev_b32_e32 v123, 2, v24
	v_or_b32_e32 v24, 1, v90
	v_cmp_eq_u32_e32 vcc, v90, v9
	v_lshlrev_b32_e32 v106, 5, v20
	v_and_b32_e32 v74, 8, v73
	v_bitop3_b32 v25, v73, v25, 7 bitop3:0x28
	v_or_b32_e32 v63, v63, v64
	v_bitop3_b32 v20, v73, v20, 7 bitop3:0x6c
	v_lshlrev_b32_e32 v73, 1, v62
	v_add_lshl_u32 v114, v62, v31, 1
	v_add_lshl_u32 v118, v30, v90, 1
	v_add_lshl_u32 v122, v11, v30, 1
	v_lshlrev_b32_e32 v124, 2, v62
	v_or_b32_e32 v30, 2, v90
	v_cndmask_b32_e64 v62, 0, 1.0, vcc
	v_cmp_eq_u32_e32 vcc, v24, v9
	v_lshlrev_b32_e32 v112, 4, v75
	v_lshlrev_b32_e32 v75, 4, v63
	v_add_lshl_u32 v117, v90, v23, 1
	v_add_lshl_u32 v121, v11, v23, 1
	v_add_lshl_u32 v125, v90, v31, 1
	v_add_lshl_u32 v23, v11, v31, 1
	v_or_b32_e32 v31, 3, v90
	v_cndmask_b32_e64 v63, 0, 1.0, vcc
	v_cmp_eq_u32_e32 vcc, v30, v9
	v_cmp_eq_u32_e64 s[4:5], 0, v9
	v_mad_u32_u24 v37, v9, s18, 16
	v_cmp_lt_u32_e64 s[8:9], v90, v9
	v_cmp_gt_u32_e64 s[10:11], v90, v9
	v_cmp_lt_u32_e64 s[12:13], v24, v9
	v_cmp_lt_u32_e64 s[14:15], v30, v9
	v_cmp_gt_u32_e64 s[16:17], v30, v9
	v_cmp_lt_u32_e64 s[18:19], v31, v9
	v_cmp_gt_u32_e64 s[20:21], v31, v9
	v_cndmask_b32_e64 v64, 0, 1.0, vcc
	v_cmp_eq_u32_e32 vcc, v31, v9
	v_lshlrev_b32_e32 v9, 2, v9
	v_lshl_add_u32 v24, v38, 10, s97
	s_mov_b32 s3, 0xdc00
	v_add3_u32 v126, v24, v9, s3
	v_and_b32_e32 v9, 3, v39
	s_movk_i32 s25, 0x2400
	v_lshlrev_b32_e32 v43, 2, v21
	v_lshlrev_b32_e32 v21, 1, v21
	v_lshl_or_b32 v9, v9, 3, s29
	v_lshlrev_b32_e32 v24, 1, v41
	s_waitcnt lgkmcnt(0)
	s_barrier
	v_lshlrev_b32_e32 v66, 2, v89
	v_or_b32_e32 v25, v25, v74
	v_or_b32_e32 v20, v20, v74
	v_add3_u32 v128, v9, v24, s25
	v_mov_b32_e32 v9, 0x3540
	v_add_u32_e32 v151, v67, v8
	v_add_u32_e32 v8, 0, v21
	s_mov_b32 s39, 0
	v_and_b32_e32 v102, 48, v39
	v_lshlrev_b32_e32 v26, 4, v26
	v_lshlrev_b32_e32 v42, 4, v42
	v_lshlrev_b32_e32 v25, 4, v25
	v_lshlrev_b32_e32 v20, 4, v20
	v_lshlrev_b32_e32 v74, 1, v65
	v_add_lshl_u32 v22, v37, v90, 1
	v_add_lshl_u32 v11, v11, v37, 1
	v_writelane_b32 v255, s97, 32
	v_lshl_or_b32 v129, v38, 4, v9
	s_add_i32 s3, 0, 0x15c00
	s_add_i32 s88, s22, 0
	s_add_i32 s89, s23, 0
	s_add_i32 s90, s24, 0
	v_add_u32_e32 v9, 0, v66
	v_add_u32_e32 v152, 0x12800, v8
	v_mbcnt_lo_u32_b32 v8, -1, 0
	s_mov_b64 s[52:53], s[38:39]
	v_add_u32_e32 v107, s70, v89
	v_lshlrev_b32_e32 v45, 4, v45
	v_cndmask_b32_e64 v65, 0, 1.0, vcc
	v_add_u32_e32 v127, 0x2d00, v103
	v_writelane_b32 v255, s29, 44
	v_or_b32_e32 v130, 0x3500, v102
	v_add_u32_e32 v131, v28, v68
	v_add_u32_e32 v132, v28, v26
	v_add_u32_e32 v133, v29, v42
	v_add_u32_e32 v134, v29, v69
	v_add_u32_e32 v135, s3, v70
	v_add_u32_e32 v136, s3, v71
	s_mov_b32 s86, 0x4038aa3b
	s_add_i32 s67, 0, 0x10000
	v_add_u32_e32 v137, v28, v72
	v_add_u32_e32 v138, v28, v25
	v_add_u32_e32 v139, v29, v75
	v_add_u32_e32 v140, v29, v20
	v_add_u32_e32 v141, s3, v73
	v_add_u32_e32 v142, s3, v74
	v_add_u32_e32 v143, v32, v33
	v_add_u32_e32 v145, v34, v35
	s_mov_b32 s87, 0xbfb8aa3b
	v_add_u32_e32 v146, v36, v44
	s_add_i32 s88, s88, 0x23900
	s_add_i32 s89, s89, 0x23900
	s_add_i32 s90, s90, 0x23900
	s_add_i32 s91, 0, 0x27900
	s_add_i32 s92, s81, 0x400
	s_add_i32 s93, s81, 0x800
	s_add_i32 s94, s81, 0xc00
	s_add_i32 s95, s81, 0x1400
	s_add_i32 s96, s81, 0x1800
	s_add_i32 s97, s81, 0x1c00
	s_add_i32 s3, 0, 0x16100
	s_add_i32 s69, 0, 0x18500
	v_mov_b32_e32 v147, 0xbf92477c
	v_add_u32_e32 v148, v40, v27
	s_xor_b64 s[54:55], s[26:27], -1
	v_add_u32_e32 v149, 0, v43
	v_add_u32_e32 v150, 0x12400, v9
	v_mov_b32_e32 v153, 0x3a27c5ac
	v_mbcnt_hi_u32_b32 v144, -1, v8
	v_add_u32_e32 v154, s71, v22
	v_add_u32_e32 v155, s71, v23
	v_add_u32_e32 v156, s71, v11
	s_mov_b32 s33, s28
	s_mov_b32 s29, 0
	v_add_u32_e32 v232, s69, v118
	v_add_u32_e32 v220, v91, v111
	v_add_u32_e32 v229, s3, v117
	v_xor_b32_e32 v242, 16, v144
	v_and_b32_e32 v241, 64, v144
	v_add_u32_e32 v21, 64, v241
	v_cmp_lt_i32_e32 vcc, v242, v21
	s_nop 1
	v_cndmask_b32_e32 v20, v144, v242, vcc
	v_lshlrev_b32_e32 v221, 2, v20
	v_add_u32_e32 v215, v92, v111
	v_add_u32_e32 v223, s67, v113
	v_add_u32_e32 v239, 0x12600, v97
	v_add_u32_e32 v236, s69, v121
	v_add_u32_e32 v208, v94, v108
	v_add_u32_e32 v210, v96, v108
	v_add_u32_e32 v218, v96, v112
	v_add_u32_e32 v237, s3, v122
	v_xor_b32_e32 v243, 32, v144
	v_add_u32_e32 v209, v95, v108
	v_cmp_lt_i32_e32 vcc, v243, v21
	s_nop 1
	v_cndmask_b32_e32 v22, v144, v243, vcc
	v_lshlrev_b32_e32 v222, 2, v22
	v_add_u32_e32 v228, s67, v116
	v_add_u32_e32 v213, s67, v109
	v_add_u32_e32 v212, v91, v45
	v_add_u32_e32 v207, v92, v45
	v_add_u32_e32 v225, 0x15d80, v44
	v_add_u32_e32 v230, s69, v117
	v_add_u32_e32 v235, s3, v121
	v_add_u32_e32 v216, v94, v112
	v_add_u32_e32 v227, s67, v115
	v_add_u32_e32 v238, s69, v122
	v_add_u32_e32 v211, v93, v45
	v_add_u32_e32 v224, s71, v114
	v_add_u32_e32 v214, s71, v110
	v_add_u32_e32 v231, s3, v118
	v_add_u32_e32 v233, s67, v119
	v_or_b32_e32 v240, v102, v241
	v_add_u32_e32 v219, v93, v111
	v_add_u32_e32 v217, v95, v112
	v_add_u32_e32 v234, s67, v120
	v_add_u32_e32 v226, s83, v102
	s_waitcnt vmcnt(0)
